# attention loops: v_pk_fma_f32 between MFMAs split into scalar v_fma_f32 pairs (15 sites)
# speedup vs baseline: 1.0113x; 1.0016x over previous
; __device__ __forceinline__ void finishSM(f32x16& p0, f32x16& p1, float alpha, float& l_reg, bf16x8& pa0, bf16x8& pa1, bf16x8& pa2, bf16x8& pa3) {
; #pragma unroll
;   for (int r = 0; r < 16; ++r) p1[r] = __builtin_amdgcn_exp2f(p1[r]);
;   float ps = 0;
; #pragma unroll
;   for (int r = 0; r < 16; ++r) ps += p0[r];
; #pragma unroll
;   for (int r = 0; r < 16; ++r) ps += p1[r];
;   { auto rr = __builtin_amdgcn_permlane32_swap(__float_as_uint(ps), __float_as_uint(ps), false, false);
;     ps = __uint_as_float(rr[0]) + __uint_as_float(rr[1]); }
;   l_reg = l_reg * alpha + ps;
;     ...
;   PK4(p0, 0, pa0); PK4(p0, 8, pa1); PK4(p1, 0, pa2); PK4(p1, 8, pa3);
; template <int DQK> __device__ __forceinline__ void qkt(f32x16& p0, f32x16& p1, const bf16_t* Ks, const char* KRs, const char* QRw, const bf16x8* qr, int r32, int hi) {
;   p0 = f32x16{}; p1 = f32x16{};
; #pragma unroll
;   for (int d0 = 0; d0 < 8; ++d0) { int cb = (d0 * 16 + hi * 8) * 2;
;     bf16x8 b0 = *reinterpret_cast<const bf16x8*>((const char*)Ks + KSWZ(r32, cb));
;     bf16x8 b1 = *reinterpret_cast<const bf16x8*>((const char*)Ks + KSWZ(32 + r32, cb));
;     p0 = __builtin_amdgcn_mfma_f32_32x32x16_bf16(b0, qr[d0], p0, 0, 0, 0);
;     p1 = __builtin_amdgcn_mfma_f32_32x32x16_bf16(b1, qr[d0], p1, 0, 0, 0); }
;   if constexpr (DQK == 192) {
; #pragma unroll
;     for (int d0 = 0; d0 < 4; ++d0) { int cb = (d0 * 16 + hi * 8) * 2;
;       bf16x8 b0 = *reinterpret_cast<const bf16x8*>(KRs + KRSWZ(r32, cb));
;       bf16x8 b1 = *reinterpret_cast<const bf16x8*>(KRs + KRSWZ(32 + r32, cb));
;       bf16x8 qx = *reinterpret_cast<const bf16x8*>(QRw + KRSWZ(r32, cb));
;       p0 = __builtin_amdgcn_mfma_f32_32x32x16_bf16(b0, qx, p0, 0, 0, 0);
;       p1 = __builtin_amdgcn_mfma_f32_32x32x16_bf16(b1, qx, p1, 0, 0, 0); }
.LBB0_343:
	ds_read_b128 v[98:101], v183 offset:58880
	ds_read_b128 v[102:105], v183 offset:50176
	ds_read_b128 v[162:165], v183 offset:50208
	ds_read_b128 v[172:175], v183 offset:58912
	s_add_i32 s2, 0, 0x12c00
	v_add_u32_e32 v221, s2, v188
	s_waitcnt lgkmcnt(2)
	v_mfma_f32_32x32x16_bf16 v[114:129], v[102:105], v[142:145], 0
	v_add_u32_e32 v222, s2, v190
	v_add_u32_e32 v223, s2, v192
	v_add_u32_e32 v228, s2, v216
	v_exp_f32_e32 v82, v82
	v_exp_f32_e32 v83, v83
	v_exp_f32_e32 v84, v84
	v_exp_f32_e32 v85, v85
	v_mfma_f32_32x32x16_bf16 v[98:113], v[98:101], v[142:145], 0
	v_exp_f32_e32 v234, v96
	v_exp_f32_e32 v235, v97
	s_waitcnt lgkmcnt(1)
	v_mfma_f32_32x32x16_bf16 v[114:129], v[162:165], v[134:137], v[114:129]
	s_waitcnt lgkmcnt(0)
	v_mfma_f32_32x32x16_bf16 v[98:113], v[172:175], v[134:137], v[98:113]
	ds_read_b128 v[162:165], v183 offset:50240
	ds_read_b128 v[172:175], v183 offset:58944
	s_waitcnt lgkmcnt(1)
	v_mfma_f32_32x32x16_bf16 v[114:129], v[162:165], v[158:161], v[114:129]
	s_waitcnt lgkmcnt(0)
	v_mfma_f32_32x32x16_bf16 v[98:113], v[172:175], v[158:161], v[98:113]
	ds_read_b128 v[162:165], v183 offset:50272
	ds_read_b128 v[172:175], v183 offset:58976
	s_waitcnt lgkmcnt(1)
	v_mfma_f32_32x32x16_bf16 v[114:129], v[162:165], v[154:157], v[114:129]
	s_waitcnt lgkmcnt(0)
	v_mfma_f32_32x32x16_bf16 v[98:113], v[172:175], v[154:157], v[98:113]
	ds_read_b128 v[162:165], v183 offset:50304
	ds_read_b128 v[172:175], v183 offset:59008
	s_waitcnt lgkmcnt(1)
	v_mfma_f32_32x32x16_bf16 v[114:129], v[162:165], v[150:153], v[114:129]
	s_waitcnt lgkmcnt(0)
	v_mfma_f32_32x32x16_bf16 v[98:113], v[172:175], v[150:153], v[98:113]
	ds_read_b128 v[162:165], v183 offset:50336
	ds_read_b128 v[172:175], v183 offset:59040
	s_waitcnt lgkmcnt(1)
	v_mfma_f32_32x32x16_bf16 v[114:129], v[162:165], v[146:149], v[114:129]
	s_waitcnt lgkmcnt(0)
	v_mfma_f32_32x32x16_bf16 v[98:113], v[172:175], v[146:149], v[98:113]
	ds_read_b128 v[162:165], v183 offset:50368
	ds_read_b128 v[172:175], v183 offset:59072
	s_waitcnt lgkmcnt(1)
	v_mfma_f32_32x32x16_bf16 v[114:129], v[162:165], v[138:141], v[114:129]
	s_waitcnt lgkmcnt(0)
	v_mfma_f32_32x32x16_bf16 v[98:113], v[172:175], v[138:141], v[98:113]
	ds_read_b128 v[162:165], v183 offset:50400
	ds_read_b128 v[172:175], v183 offset:59104
	s_waitcnt lgkmcnt(1)
	v_mfma_f32_32x32x16_bf16 v[114:129], v[162:165], v[130:133], v[114:129]
	ds_read_b128 v[162:165], v221
	s_waitcnt lgkmcnt(1)
	v_mfma_f32_32x32x16_bf16 v[98:113], v[172:175], v[130:133], v[98:113]
	ds_read_b128 v[172:175], v222
	ds_read_b128 v[224:227], v184
	ds_read_b128 v[230:233], v184 offset:32
	s_waitcnt lgkmcnt(1)
	v_mfma_f32_32x32x16_bf16 v[114:129], v[162:165], v[224:227], v[114:129]
	ds_read_b128 v[162:165], v223
	v_mfma_f32_32x32x16_bf16 v[98:113], v[172:175], v[224:227], v[98:113]
	v_add_u32_e32 v224, s2, v198
	ds_read_b128 v[172:175], v224
	v_add_u32_e32 v225, s2, v210
	v_add_u32_e32 v226, s2, v212
	v_add_u32_e32 v227, s2, v214
	s_waitcnt lgkmcnt(1)
	v_mfma_f32_32x32x16_bf16 v[114:129], v[162:165], v[230:233], v[114:129]
	ds_read_b128 v[162:165], v225
	s_waitcnt lgkmcnt(1)
	v_mfma_f32_32x32x16_bf16 v[98:113], v[172:175], v[230:233], v[98:113]
	ds_read_b128 v[172:175], v226
	ds_read_b128 v[230:233], v184 offset:64
	s_waitcnt lgkmcnt(0)
	v_mfma_f32_32x32x16_bf16 v[114:129], v[162:165], v[230:233], v[114:129]
	ds_read_b128 v[162:165], v227
	v_mfma_f32_32x32x16_bf16 v[98:113], v[172:175], v[230:233], v[98:113]
	ds_read_b128 v[172:175], v228
	ds_read_b128 v[230:233], v184 offset:96
	s_waitcnt lgkmcnt(0)
	v_mfma_f32_32x32x16_bf16 v[114:129], v[162:165], v[230:233], v[114:129]
	v_exp_f32_e32 v162, v86
	v_add_f32_e32 v86, 0, v66
	v_add_f32_e32 v86, v67, v86
	v_add_f32_e32 v86, v68, v86
	v_add_f32_e32 v86, v69, v86
	v_add_f32_e32 v86, v70, v86
	v_add_f32_e32 v86, v71, v86
	v_add_f32_e32 v86, v72, v86
	v_add_f32_e32 v86, v73, v86
	v_add_f32_e32 v86, v74, v86
	v_add_f32_e32 v86, v75, v86
	v_add_f32_e32 v86, v76, v86
	v_add_f32_e32 v86, v77, v86
	v_add_f32_e32 v86, v78, v86
	v_add_f32_e32 v86, v79, v86
	v_add_f32_e32 v86, v80, v86
	v_add_f32_e32 v86, v81, v86
	v_add_f32_e32 v86, v82, v86
	v_exp_f32_e32 v163, v87
	v_add_f32_e32 v86, v83, v86
	v_exp_f32_e32 v164, v88
	v_add_f32_e32 v86, v84, v86
	v_exp_f32_e32 v165, v89
	v_add_f32_e32 v86, v85, v86
	v_mfma_f32_32x32x16_bf16 v[98:113], v[172:175], v[230:233], v[98:113]
	v_exp_f32_e32 v172, v90
	v_add_f32_e32 v86, v162, v86
	v_exp_f32_e32 v173, v91
	v_add_f32_e32 v86, v163, v86
	v_exp_f32_e32 v174, v92
	v_add_f32_e32 v86, v164, v86
	v_exp_f32_e32 v175, v93
	v_add_f32_e32 v86, v165, v86
	v_exp_f32_e32 v232, v94
	v_add_f32_e32 v86, v172, v86
	v_exp_f32_e32 v233, v95
	v_add_f32_e32 v86, v173, v86
	v_add_f32_e32 v86, v174, v86
	v_add_f32_e32 v86, v175, v86
	v_add_f32_e32 v86, v232, v86
	v_add_f32_e32 v86, v233, v86
	v_add_f32_e32 v86, v234, v86
	v_add_f32_e32 v230, v235, v86
	v_mov_b32_e32 v231, v230
	s_nop 1
	v_permlane32_swap_b32_e32 v230, v231
	v_cvt_pk_bf16_f32 v86, v66, v67
	v_cvt_pk_bf16_f32 v87, v68, v69
	v_cvt_pk_bf16_f32 v88, v70, v71
	v_cvt_pk_bf16_f32 v89, v72, v73
	v_cvt_pk_bf16_f32 v90, v74, v75
	v_cvt_pk_bf16_f32 v91, v76, v77
	v_cvt_pk_bf16_f32 v92, v78, v79
	v_cvt_pk_bf16_f32 v93, v80, v81
	v_cvt_pk_bf16_f32 v94, v82, v83
	v_cvt_pk_bf16_f32 v95, v84, v85
	v_cvt_pk_bf16_f32 v96, v162, v163
	v_cvt_pk_bf16_f32 v97, v164, v165
	v_cvt_pk_bf16_f32 v162, v172, v173
	v_cvt_pk_bf16_f32 v163, v174, v175
	v_cvt_pk_bf16_f32 v164, v232, v233
	v_cvt_pk_bf16_f32 v165, v234, v235
	v_permlane32_swap_b32_e32 v86, v88
	v_permlane32_swap_b32_e32 v87, v89
	v_permlane32_swap_b32_e32 v90, v92
	v_permlane32_swap_b32_e32 v91, v93
	v_permlane32_swap_b32_e32 v94, v96
	v_permlane32_swap_b32_e32 v95, v97
	v_permlane32_swap_b32_e32 v162, v164
	v_permlane32_swap_b32_e32 v163, v165
	v_lshl_add_u64 v[172:173], s[92:93], 0, v[170:171]
	s_mov_b32 s2, 0xd880000
	v_add_co_u32_e32 v70, vcc, s2, v172
	s_mov_b32 s2, 0xd8a0000
	s_nop 0
	v_addc_co_u32_e32 v71, vcc, 0, v173, vcc
	v_add_co_u32_e32 v74, vcc, s2, v172
	v_lshl_add_u64 v[174:175], s[92:93], 0, v[168:169]
	s_nop 0
	v_addc_co_u32_e32 v75, vcc, 0, v173, vcc
	global_load_dwordx4 v[66:69], v[70:71], off offset:256
	s_nop 0
	global_load_dwordx4 v[70:73], v[70:71], off
	s_nop 0
	global_load_dwordx4 v[78:81], v[74:75], off offset:256
	s_nop 0
	global_load_dwordx4 v[74:77], v[74:75], off
	s_mov_b32 s2, 0x19804000
	v_add_co_u32_e32 v82, vcc, s2, v174
	s_nop 1
	v_addc_co_u32_e32 v83, vcc, 0, v175, vcc
	global_load_dwordx4 v[82:85], v[82:83], off
	ds_read_b64_tr_b16 v[232:233], v182 offset:0
	ds_read_b64_tr_b16 v[234:235], v182 offset:0x800
	ds_read_b64_tr_b16 v[236:237], v182 offset:0x1000
	ds_read_b64_tr_b16 v[238:239], v182 offset:0x1800
	ds_read_b64_tr_b16 v[240:241], v182 offset:0x2000
	ds_read_b64_tr_b16 v[242:243], v182 offset:0x2800
	ds_read_b64_tr_b16 v[244:245], v182 offset:0x3000
	ds_read_b64_tr_b16 v[246:247], v182 offset:0x3800
	s_waitcnt lgkmcnt(0)
; #define SBAR() __builtin_amdgcn_sched_barrier(0)
; #define SWAIT() do { if constexpr (SD == 1) asm volatile("s_waitcnt vmcnt(0)" ::: "memory"); else asm volatile("s_waitcnt vmcnt(4)" ::: "memory"); } while (0)
; #define RESC(a) do { if (__any((a) < 1.f)) { if (hi == 0) al_l[r32] = (a); asm volatile("s_waitcnt lgkmcnt(0)" ::: "memory"); \
;     _Pragma("unroll") for (int d = 0; d < 4; ++d) _Pragma("unroll") for (int r = 0; r < 16; ++r) o[d][r] *= al_l[crow(r, hi)]; } } while (0)
; template <int DQK> __device__ __forceinline__ void pv_partialSM(f32x16* o, int vb, bf16x8 pa0, bf16x8 pa1, bf16x8 pa2, bf16x8 pa3,
;                                                                  f32x16& p0, f32x16& p1, float& m_reg, float& alpha) {
;     ...
;   pv_one<0>(o[0], vb, pa0, pa1, pa2, pa3);
;   float pmax = p0[0];
; #pragma unroll
;   for (int r = 1; r < 16; ++r) pmax = fmaxf(pmax, p0[r]);
;   pv_one<1>(o[1], vb, pa0, pa1, pa2, pa3);
; #pragma unroll
;   for (int r = 0; r < 16; ++r) pmax = fmaxf(pmax, p1[r]);
;   { auto rr = __builtin_amdgcn_permlane32_swap(__float_as_uint(pmax), __float_as_uint(pmax), false, false);
;     pmax = fmaxf(__uint_as_float(rr[0]), __uint_as_float(rr[1])); }
;   const bool keep = __all(pmax - m_reg <= THR / SCALE);
;   const float mn = keep ? m_reg : fmaxf(m_reg, pmax);
;   alpha = __builtin_amdgcn_exp2f((m_reg - mn) * C); m_reg = mn;
;   const float mnC = -mn * C;
;   pv_one<2>(o[2], vb, pa0, pa1, pa2, pa3);
; #pragma unroll
;   for (int r = 0; r < 16; ++r) { p0[r] = fmaf(p0[r], C, mnC); p1[r] = fmaf(p1[r], C, mnC); }
;   pv_one<3>(o[3], vb, pa0, pa1, pa2, pa3);
; #pragma unroll
;   for (int r = 0; r < 16; ++r) p0[r] = __builtin_amdgcn_exp2f(p0[r]);
;   asm volatile("" : "+v"(p0), "+v"(p1));
;   SBAR();
; template <int DQK, int LDK> ...
;     ...
;     __syncthreads(); SWAIT(); SWRITE(0, SE);
;     RESC(alB); __syncthreads();
	s_nop 0
	v_mfma_f32_32x32x16_bf16 v[2:17], v[86:89], v[232:235], v[2:17]
	v_max_f32_e32 v232, v115, v115
	v_max_f32_e32 v233, v114, v114
	v_max_f32_e32 v232, v233, v232
	v_max3_f32 v232, v232, v116, v117
	v_max3_f32 v232, v232, v118, v119
	v_max3_f32 v232, v232, v120, v121
	v_max3_f32 v232, v232, v122, v123
	v_mfma_f32_32x32x16_bf16 v[2:17], v[90:93], v[236:239], v[2:17]
	v_max3_f32 v232, v232, v124, v125
	v_max3_f32 v232, v232, v126, v127
	v_max3_f32 v248, v232, v128, v129
	ds_read_b64_tr_b16 v[232:233], v182 offset:0x200
	ds_read_b64_tr_b16 v[234:235], v182 offset:0xa00
	ds_read_b64_tr_b16 v[236:237], v182 offset:0x1200
	ds_read_b64_tr_b16 v[238:239], v182 offset:0x1a00
	v_mfma_f32_32x32x16_bf16 v[2:17], v[94:97], v[240:243], v[2:17]
	ds_read_b64_tr_b16 v[240:241], v182 offset:0x2200
	ds_read_b64_tr_b16 v[242:243], v182 offset:0x2a00
	v_mfma_f32_32x32x16_bf16 v[2:17], v[162:165], v[244:247], v[2:17]
	ds_read_b64_tr_b16 v[244:245], v182 offset:0x3200
	ds_read_b64_tr_b16 v[246:247], v182 offset:0x3a00
	s_waitcnt lgkmcnt(0)
	v_mfma_f32_32x32x16_bf16 v[50:65], v[86:89], v[232:235], v[50:65]
	v_max3_f32 v248, v248, v98, v99
	v_max3_f32 v248, v248, v100, v101
	v_max3_f32 v248, v248, v102, v103
	v_max3_f32 v248, v248, v104, v105
	v_max3_f32 v248, v248, v106, v107
	v_max3_f32 v232, v248, v108, v109
	v_max3_f32 v232, v232, v110, v111
	v_mfma_f32_32x32x16_bf16 v[50:65], v[90:93], v[236:239], v[50:65]
	v_max3_f32 v232, v232, v112, v113
	v_mov_b32_e32 v233, v232
	s_nop 1
	v_permlane32_swap_b32_e32 v232, v233
	v_max_f32_e32 v233, v233, v233
	v_max_f32_e32 v232, v232, v232
	v_max_f32_e32 v232, v232, v233
	v_mfma_f32_32x32x16_bf16 v[50:65], v[94:97], v[240:243], v[50:65]
	v_sub_f32_e32 v233, v232, v229
	ds_read_b64_tr_b16 v[234:235], v182 offset:0x400
	v_cmp_ge_f32_e32 vcc, s21, v233
	ds_read_b64_tr_b16 v[236:237], v182 offset:0xc00
	s_cmp_eq_u64 vcc, exec
	v_max_f32_e32 v233, v229, v229
	ds_read_b64_tr_b16 v[238:239], v182 offset:0x1400
	v_max_f32_e32 v232, v233, v232
	s_cselect_b64 vcc, -1, 0
	v_mfma_f32_32x32x16_bf16 v[50:65], v[162:165], v[244:247], v[50:65]
	ds_read_b64_tr_b16 v[240:241], v182 offset:0x1c00
	v_cndmask_b32_e32 v233, v232, v229, vcc
	ds_read_b64_tr_b16 v[242:243], v182 offset:0x2400
	v_sub_f32_e32 v229, v229, v233
	ds_read_b64_tr_b16 v[244:245], v182 offset:0x2c00
	v_mul_f32_e32 v229, 0x3dd53b94, v229
	ds_read_b64_tr_b16 v[246:247], v182 offset:0x3400
	v_exp_f32_e32 v232, v229
	ds_read_b64_tr_b16 v[248:249], v182 offset:0x3c00
	s_waitcnt lgkmcnt(0)
	v_mul_f32_e32 v250, 0xbdd53b94, v233
	v_mfma_f32_32x32x16_bf16 v[34:49], v[86:89], v[234:237], v[34:49]
	v_fmamk_f32 v229, v114, 0x3dd53b94, v250
	v_fmamk_f32 v234, v115, 0x3dd53b94, v250
	v_fma_f32 v114, v98, s36, v250
	v_fma_f32 v115, v99, s36, v250
	ds_read_b64_tr_b16 v[98:99], v182 offset:0x600
	v_fmamk_f32 v235, v116, 0x3dd53b94, v250
	v_fmamk_f32 v236, v117, 0x3dd53b94, v250
	v_fma_f32 v116, v100, s36, v250
	v_fma_f32 v117, v101, s36, v250
	v_mfma_f32_32x32x16_bf16 v[34:49], v[90:93], v[238:241], v[34:49]
	ds_read_b64_tr_b16 v[100:101], v182 offset:0xe00
	v_fmamk_f32 v237, v118, 0x3dd53b94, v250
	v_fmamk_f32 v238, v119, 0x3dd53b94, v250
	v_fma_f32 v118, v102, s36, v250
	v_fma_f32 v119, v103, s36, v250
	ds_read_b64_tr_b16 v[102:103], v182 offset:0x1600
	v_fmamk_f32 v239, v120, 0x3dd53b94, v250
	v_fmamk_f32 v240, v121, 0x3dd53b94, v250
	v_mfma_f32_32x32x16_bf16 v[34:49], v[94:97], v[242:245], v[34:49]
	v_fma_f32 v120, v104, s36, v250
	v_fma_f32 v121, v105, s36, v250
	ds_read_b64_tr_b16 v[104:105], v182 offset:0x1e00
	v_fmamk_f32 v241, v122, 0x3dd53b94, v250
	v_fmamk_f32 v242, v123, 0x3dd53b94, v250
	v_fma_f32 v122, v106, s36, v250
	v_fma_f32 v123, v107, s36, v250
	ds_read_b64_tr_b16 v[106:107], v182 offset:0x2600
	v_fmamk_f32 v243, v124, 0x3dd53b94, v250
	v_mfma_f32_32x32x16_bf16 v[34:49], v[162:165], v[246:249], v[34:49]
	v_fmamk_f32 v244, v125, 0x3dd53b94, v250
	v_fma_f32 v124, v108, s36, v250
	v_fma_f32 v125, v109, s36, v250
	ds_read_b64_tr_b16 v[108:109], v182 offset:0x2e00
	v_fmamk_f32 v245, v126, 0x3dd53b94, v250
	v_fmamk_f32 v246, v127, 0x3dd53b94, v250
	v_mov_b32_e32 v248, v250
	v_fma_f32 v126, v110, s36, v250
	v_fma_f32 v127, v111, s36, v250
	ds_read_b64_tr_b16 v[110:111], v182 offset:0x3600
	v_fmamk_f32 v247, v128, 0x3dd53b94, v250
	v_fmac_f32_e32 v248, 0x3dd53b94, v129
	v_fma_f32 v128, v112, s36, v250
	v_fma_f32 v129, v113, s36, v250
	ds_read_b64_tr_b16 v[112:113], v182 offset:0x3e00
	s_waitcnt lgkmcnt(0)
	v_mfma_f32_32x32x16_bf16 v[18:33], v[86:89], v[98:101], v[18:33]
	v_exp_f32_e32 v98, v229
	v_exp_f32_e32 v99, v234
	v_exp_f32_e32 v100, v235
	v_exp_f32_e32 v101, v236
	v_mfma_f32_32x32x16_bf16 v[18:33], v[90:93], v[102:105], v[18:33]
	v_exp_f32_e32 v102, v237
	v_exp_f32_e32 v103, v238
	v_exp_f32_e32 v104, v239
	v_exp_f32_e32 v105, v240
	v_mfma_f32_32x32x16_bf16 v[18:33], v[94:97], v[106:109], v[18:33]
	v_exp_f32_e32 v106, v241
	v_exp_f32_e32 v107, v242
	v_exp_f32_e32 v108, v243
	v_exp_f32_e32 v109, v244
	v_mfma_f32_32x32x16_bf16 v[18:33], v[162:165], v[110:113], v[18:33]
	v_exp_f32_e32 v110, v245
	v_exp_f32_e32 v111, v246
	v_exp_f32_e32 v112, v247
	v_exp_f32_e32 v113, v248
	s_barrier
	s_waitcnt vmcnt(0)
	s_waitcnt vmcnt(4)
	ds_write_b128 v185, v[66:69]
	s_waitcnt vmcnt(2)
	ds_write_b128 v186, v[78:81]
	ds_write_b128 v187, v[70:73] offset:32768
	s_waitcnt vmcnt(1)
	ds_write_b128 v187, v[74:77] offset:41472
	v_add_u32_e32 v66, 0x10800, v218
	v_cmp_gt_f32_e32 vcc, 1.0, v232
	s_waitcnt vmcnt(0)
	ds_write_b128 v66, v[82:85]
	s_cbranch_vccz .LBB0_347
; template <int DQK> __device__ __forceinline__ void qkt(f32x16& p0, f32x16& p1, const bf16_t* Ks, const char* KRs, const char* QRw, const bf16x8* qr, int r32, int hi) {
;   p0 = f32x16{}; p1 = f32x16{};
; #pragma unroll
;   for (int d0 = 0; d0 < 8; ++d0) { int cb = (d0 * 16 + hi * 8) * 2;
;     bf16x8 b0 = *reinterpret_cast<const bf16x8*>((const char*)Ks + KSWZ(r32, cb));
;     bf16x8 b1 = *reinterpret_cast<const bf16x8*>((const char*)Ks + KSWZ(32 + r32, cb));
;     p0 = __builtin_amdgcn_mfma_f32_32x32x16_bf16(b0, qr[d0], p0, 0, 0, 0);
;     p1 = __builtin_amdgcn_mfma_f32_32x32x16_bf16(b1, qr[d0], p1, 0, 0, 0); }
;   if constexpr (DQK == 192) {
; #pragma unroll
;     for (int d0 = 0; d0 < 4; ++d0) { int cb = (d0 * 16 + hi * 8) * 2;
;       bf16x8 b0 = *reinterpret_cast<const bf16x8*>(KRs + KRSWZ(r32, cb));
;       bf16x8 b1 = *reinterpret_cast<const bf16x8*>(KRs + KRSWZ(32 + r32, cb));
;       bf16x8 qx = *reinterpret_cast<const bf16x8*>(QRw + KRSWZ(r32, cb));
;       p0 = __builtin_amdgcn_mfma_f32_32x32x16_bf16(b0, qx, p0, 0, 0, 0);
;       p1 = __builtin_amdgcn_mfma_f32_32x32x16_bf16(b1, qx, p1, 0, 0, 0); }
	s_and_saveexec_b64 s[2:3], s[40:41]
	ds_write_b32 v179, v232 offset:128
	s_or_b64 exec, exec, s[2:3]
	s_waitcnt lgkmcnt(0)
	v_add_u32_e32 v78, s14, v0
	ds_read_b128 v[66:69], v78 offset:224
	ds_read_b128 v[70:73], v78 offset:192
	ds_read_b128 v[74:77], v78 offset:160
	ds_read_b128 v[78:81], v78 offset:128
	s_waitcnt lgkmcnt(3)
	v_pk_mul_f32 v[14:15], v[14:15], v[66:67]
	s_waitcnt lgkmcnt(2)
	v_pk_mul_f32 v[10:11], v[10:11], v[70:71]
	s_waitcnt lgkmcnt(1)
	v_pk_mul_f32 v[6:7], v[6:7], v[74:75]
	v_pk_mul_f32 v[16:17], v[16:17], v[68:69]
	v_pk_mul_f32 v[12:13], v[12:13], v[72:73]
	v_pk_mul_f32 v[8:9], v[8:9], v[76:77]
	s_waitcnt lgkmcnt(0)
	v_pk_mul_f32 v[4:5], v[4:5], v[80:81]
	v_pk_mul_f32 v[2:3], v[2:3], v[78:79]
	v_pk_mul_f32 v[62:63], v[62:63], v[66:67]
	v_pk_mul_f32 v[58:59], v[58:59], v[70:71]
	v_pk_mul_f32 v[54:55], v[54:55], v[74:75]
	v_pk_mul_f32 v[64:65], v[64:65], v[68:69]
	v_pk_mul_f32 v[60:61], v[60:61], v[72:73]
	v_pk_mul_f32 v[56:57], v[56:57], v[76:77]
	v_pk_mul_f32 v[52:53], v[52:53], v[80:81]
	v_pk_mul_f32 v[50:51], v[50:51], v[78:79]
	v_pk_mul_f32 v[46:47], v[46:47], v[66:67]
	v_pk_mul_f32 v[42:43], v[42:43], v[70:71]
	v_pk_mul_f32 v[38:39], v[38:39], v[74:75]
	v_pk_mul_f32 v[48:49], v[48:49], v[68:69]
	v_pk_mul_f32 v[44:45], v[44:45], v[72:73]
	v_pk_mul_f32 v[40:41], v[40:41], v[76:77]
	v_pk_mul_f32 v[36:37], v[36:37], v[80:81]
	v_pk_mul_f32 v[34:35], v[34:35], v[78:79]
	v_pk_mul_f32 v[30:31], v[30:31], v[66:67]
	v_pk_mul_f32 v[26:27], v[26:27], v[70:71]
	v_pk_mul_f32 v[22:23], v[22:23], v[74:75]
	v_pk_mul_f32 v[32:33], v[32:33], v[68:69]
	v_pk_mul_f32 v[28:29], v[28:29], v[72:73]
	v_pk_mul_f32 v[24:25], v[24:25], v[76:77]
	v_pk_mul_f32 v[20:21], v[20:21], v[80:81]
	v_pk_mul_f32 v[18:19], v[18:19], v[78:79]
.LBB0_347:
	s_waitcnt lgkmcnt(0)
	s_barrier
	ds_read_b128 v[66:69], v183 offset:41472
	ds_read_b128 v[70:73], v183 offset:32768
	ds_read_b128 v[162:165], v183 offset:32800
	ds_read_b128 v[234:237], v183 offset:41504
	v_exp_f32_e32 v114, v114
	v_exp_f32_e32 v115, v115
	s_waitcnt lgkmcnt(2)
	v_mfma_f32_32x32x16_bf16 v[82:97], v[70:73], v[142:145], 0
	v_exp_f32_e32 v116, v116
	v_exp_f32_e32 v117, v117
	v_exp_f32_e32 v229, v122
	v_cvt_pk_bf16_f32 v122, v106, v107
	v_mfma_f32_32x32x16_bf16 v[66:81], v[66:69], v[142:145], 0
	s_waitcnt lgkmcnt(1)
	v_mfma_f32_32x32x16_bf16 v[82:97], v[162:165], v[134:137], v[82:97]
	s_waitcnt lgkmcnt(0)
	v_mfma_f32_32x32x16_bf16 v[66:81], v[234:237], v[134:137], v[66:81]
	ds_read_b128 v[162:165], v183 offset:32832
	ds_read_b128 v[234:237], v183 offset:41536
	s_waitcnt lgkmcnt(1)
	v_mfma_f32_32x32x16_bf16 v[82:97], v[162:165], v[158:161], v[82:97]
	s_waitcnt lgkmcnt(0)
	v_mfma_f32_32x32x16_bf16 v[66:81], v[234:237], v[158:161], v[66:81]
	ds_read_b128 v[162:165], v183 offset:32864
	ds_read_b128 v[234:237], v183 offset:41568
	s_waitcnt lgkmcnt(1)
	v_mfma_f32_32x32x16_bf16 v[82:97], v[162:165], v[154:157], v[82:97]
	s_waitcnt lgkmcnt(0)
	v_mfma_f32_32x32x16_bf16 v[66:81], v[234:237], v[154:157], v[66:81]
	ds_read_b128 v[162:165], v183 offset:32896
	ds_read_b128 v[234:237], v183 offset:41600
	s_waitcnt lgkmcnt(1)
	v_mfma_f32_32x32x16_bf16 v[82:97], v[162:165], v[150:153], v[82:97]
	s_waitcnt lgkmcnt(0)
	v_mfma_f32_32x32x16_bf16 v[66:81], v[234:237], v[150:153], v[66:81]
	ds_read_b128 v[162:165], v183 offset:32928
	ds_read_b128 v[234:237], v183 offset:41632
	s_waitcnt lgkmcnt(1)
	v_mfma_f32_32x32x16_bf16 v[82:97], v[162:165], v[146:149], v[82:97]
	s_waitcnt lgkmcnt(0)
	v_mfma_f32_32x32x16_bf16 v[66:81], v[234:237], v[146:149], v[66:81]
	ds_read_b128 v[162:165], v183 offset:32960
	ds_read_b128 v[234:237], v183 offset:41664
	s_waitcnt lgkmcnt(1)
	v_mfma_f32_32x32x16_bf16 v[82:97], v[162:165], v[138:141], v[82:97]
	s_waitcnt lgkmcnt(0)
	v_mfma_f32_32x32x16_bf16 v[66:81], v[234:237], v[138:141], v[66:81]
	ds_read_b128 v[162:165], v183 offset:32992
	ds_read_b128 v[234:237], v183 offset:41696
	s_waitcnt lgkmcnt(1)
	v_mfma_f32_32x32x16_bf16 v[82:97], v[162:165], v[130:133], v[82:97]
	s_waitcnt lgkmcnt(0)
	v_mfma_f32_32x32x16_bf16 v[66:81], v[234:237], v[130:133], v[66:81]
	ds_read_b128 v[162:165], v189
	ds_read_b128 v[234:237], v191
	ds_read_b128 v[238:241], v184
	ds_read_b128 v[242:245], v184 offset:32
	s_waitcnt lgkmcnt(1)
	v_mfma_f32_32x32x16_bf16 v[82:97], v[162:165], v[238:241], v[82:97]
	v_mfma_f32_32x32x16_bf16 v[66:81], v[234:237], v[238:241], v[66:81]
	ds_read_b128 v[162:165], v193
	ds_read_b128 v[234:237], v199
	s_waitcnt lgkmcnt(1)
	v_mfma_f32_32x32x16_bf16 v[82:97], v[162:165], v[242:245], v[82:97]
	s_waitcnt lgkmcnt(0)
	v_mfma_f32_32x32x16_bf16 v[66:81], v[234:237], v[242:245], v[66:81]
	ds_read_b128 v[162:165], v211
	ds_read_b128 v[234:237], v213
	ds_read_b128 v[238:241], v184 offset:64
	v_exp_f32_e32 v242, v129
	s_waitcnt lgkmcnt(0)
	v_mfma_f32_32x32x16_bf16 v[82:97], v[162:165], v[238:241], v[82:97]
	v_mfma_f32_32x32x16_bf16 v[66:81], v[234:237], v[238:241], v[66:81]
	ds_read_b128 v[162:165], v215
	ds_read_b128 v[234:237], v217
	ds_read_b128 v[238:241], v184 offset:96
	s_waitcnt lgkmcnt(0)
; __device__ __forceinline__ void finishSM(f32x16& p0, f32x16& p1, float alpha, float& l_reg, bf16x8& pa0, bf16x8& pa1, bf16x8& pa2, bf16x8& pa3) {
; #pragma unroll
;   for (int r = 0; r < 16; ++r) p1[r] = __builtin_amdgcn_exp2f(p1[r]);
;   float ps = 0;
; #pragma unroll
;   for (int r = 0; r < 16; ++r) ps += p0[r];
; #pragma unroll
;   for (int r = 0; r < 16; ++r) ps += p1[r];
;   { auto rr = __builtin_amdgcn_permlane32_swap(__float_as_uint(ps), __float_as_uint(ps), false, false);
;     ps = __uint_as_float(rr[0]) + __uint_as_float(rr[1]); }
;   l_reg = l_reg * alpha + ps;
;     ...
;   PK4(p0, 0, pa0); PK4(p0, 8, pa1); PK4(p1, 0, pa2); PK4(p1, 8, pa3);
; template <int DQK> __device__ __forceinline__ void pv_partialSM(f32x16* o, int vb, bf16x8 pa0, bf16x8 pa1, bf16x8 pa2, bf16x8 pa3,
;                                                                  f32x16& p0, f32x16& p1, float& m_reg, float& alpha) {
;     ...
;   pv_one<0>(o[0], vb, pa0, pa1, pa2, pa3);
;   float pmax = p0[0];
; #pragma unroll
;   for (int r = 1; r < 16; ++r) pmax = fmaxf(pmax, p0[r]);
;   pv_one<1>(o[1], vb, pa0, pa1, pa2, pa3);
; #pragma unroll
;   for (int r = 0; r < 16; ++r) pmax = fmaxf(pmax, p1[r]);
;   { auto rr = __builtin_amdgcn_permlane32_swap(__float_as_uint(pmax), __float_as_uint(pmax), false, false);
;     pmax = fmaxf(__uint_as_float(rr[0]), __uint_as_float(rr[1])); }
;   const bool keep = __all(pmax - m_reg <= THR / SCALE);
;   const float mn = keep ? m_reg : fmaxf(m_reg, pmax);
;   alpha = __builtin_amdgcn_exp2f((m_reg - mn) * C); m_reg = mn;
	v_mfma_f32_32x32x16_bf16 v[82:97], v[162:165], v[238:241], v[82:97]
	v_exp_f32_e32 v162, v118
	v_add_f32_e32 v118, 0, v98
	v_add_f32_e32 v118, v99, v118
	v_add_f32_e32 v118, v100, v118
	v_add_f32_e32 v118, v101, v118
	v_add_f32_e32 v118, v102, v118
	v_add_f32_e32 v118, v103, v118
	v_add_f32_e32 v118, v104, v118
	v_add_f32_e32 v118, v105, v118
	v_add_f32_e32 v118, v106, v118
	v_add_f32_e32 v118, v107, v118
	v_add_f32_e32 v118, v108, v118
	v_add_f32_e32 v118, v109, v118
	v_add_f32_e32 v118, v110, v118
	v_add_f32_e32 v118, v111, v118
	v_add_f32_e32 v118, v112, v118
	v_add_f32_e32 v118, v113, v118
	v_add_f32_e32 v118, v114, v118
	v_exp_f32_e32 v163, v119
	v_add_f32_e32 v118, v115, v118
	v_exp_f32_e32 v164, v120
	v_add_f32_e32 v118, v116, v118
	v_exp_f32_e32 v165, v121
	v_add_f32_e32 v118, v117, v118
	v_add_f32_e32 v118, v162, v118
	v_mfma_f32_32x32x16_bf16 v[66:81], v[234:237], v[238:241], v[66:81]
	v_exp_f32_e32 v236, v123
	v_add_f32_e32 v118, v163, v118
	v_exp_f32_e32 v237, v124
	v_add_f32_e32 v118, v164, v118
	v_exp_f32_e32 v238, v125
	v_add_f32_e32 v118, v165, v118
	v_exp_f32_e32 v239, v126
	v_add_f32_e32 v118, v229, v118
	v_exp_f32_e32 v240, v127
	v_add_f32_e32 v118, v236, v118
	v_exp_f32_e32 v241, v128
	v_add_f32_e32 v118, v237, v118
	v_add_f32_e32 v118, v238, v118
	v_add_f32_e32 v118, v239, v118
	v_add_f32_e32 v118, v240, v118
	v_add_f32_e32 v118, v241, v118
	v_add_f32_e32 v234, v242, v118
	v_mov_b32_e32 v235, v234
	s_nop 1
	v_permlane32_swap_b32_e32 v234, v235
	v_cvt_pk_bf16_f32 v118, v98, v99
	v_cvt_pk_bf16_f32 v119, v100, v101
	v_cvt_pk_bf16_f32 v120, v102, v103
	v_cvt_pk_bf16_f32 v121, v104, v105
	v_cvt_pk_bf16_f32 v123, v108, v109
	v_cvt_pk_bf16_f32 v124, v110, v111
	v_cvt_pk_bf16_f32 v125, v112, v113
	v_cvt_pk_bf16_f32 v126, v114, v115
	v_cvt_pk_bf16_f32 v127, v116, v117
	v_cvt_pk_bf16_f32 v128, v162, v163
	v_cvt_pk_bf16_f32 v129, v164, v165
	v_cvt_pk_bf16_f32 v162, v229, v236
	v_cvt_pk_bf16_f32 v163, v237, v238
	v_cvt_pk_bf16_f32 v164, v239, v240
	v_cvt_pk_bf16_f32 v165, v241, v242
	v_permlane32_swap_b32_e32 v118, v120
	v_permlane32_swap_b32_e32 v119, v121
	v_permlane32_swap_b32_e32 v122, v124
	v_permlane32_swap_b32_e32 v123, v125
	v_permlane32_swap_b32_e32 v126, v128
	v_permlane32_swap_b32_e32 v127, v129
	v_permlane32_swap_b32_e32 v162, v164
	v_permlane32_swap_b32_e32 v163, v165
	s_mov_b32 s2, 0xd8c0000
	v_add_co_u32_e32 v102, vcc, s2, v172
	s_mov_b32 s2, 0xd8e0000
	s_nop 0
	v_addc_co_u32_e32 v103, vcc, 0, v173, vcc
	v_add_co_u32_e32 v106, vcc, s2, v172
	s_mov_b32 s2, 0x19806000
	s_nop 0
	v_addc_co_u32_e32 v107, vcc, 0, v173, vcc
	global_load_dwordx4 v[98:101], v[102:103], off offset:256
	s_nop 0
	global_load_dwordx4 v[102:105], v[102:103], off
	s_nop 0
	global_load_dwordx4 v[110:113], v[106:107], off offset:256
	s_nop 0
	global_load_dwordx4 v[106:109], v[106:107], off
	v_add_co_u32_e32 v114, vcc, s2, v174
	s_nop 1
	v_addc_co_u32_e32 v115, vcc, 0, v175, vcc
	global_load_dwordx4 v[114:117], v[114:115], off
	ds_read_b64_tr_b16 v[172:173], v181 offset:0
	ds_read_b64_tr_b16 v[174:175], v181 offset:0x800
	ds_read_b64_tr_b16 v[236:237], v181 offset:0x1000
	ds_read_b64_tr_b16 v[238:239], v181 offset:0x1800
	ds_read_b64_tr_b16 v[240:241], v181 offset:0x2000
	ds_read_b64_tr_b16 v[242:243], v181 offset:0x2800
	ds_read_b64_tr_b16 v[244:245], v181 offset:0x3000
	ds_read_b64_tr_b16 v[246:247], v181 offset:0x3800
	s_waitcnt lgkmcnt(0)
	s_nop 0
	v_mfma_f32_32x32x16_bf16 v[2:17], v[118:121], v[172:175], v[2:17]
	v_max_f32_e32 v172, v83, v83
	v_max_f32_e32 v173, v82, v82
	v_max_f32_e32 v172, v173, v172
	v_max3_f32 v172, v172, v84, v85
	v_max3_f32 v172, v172, v86, v87
	v_max3_f32 v172, v172, v88, v89
	v_max3_f32 v172, v172, v90, v91
	v_mfma_f32_32x32x16_bf16 v[2:17], v[122:125], v[236:239], v[2:17]
	v_max3_f32 v172, v172, v92, v93
	v_max3_f32 v172, v172, v94, v95
	v_max3_f32 v229, v172, v96, v97
	ds_read_b64_tr_b16 v[172:173], v181 offset:0x200
	ds_read_b64_tr_b16 v[174:175], v181 offset:0xa00
	ds_read_b64_tr_b16 v[236:237], v181 offset:0x1200
	ds_read_b64_tr_b16 v[238:239], v181 offset:0x1a00
	v_mfma_f32_32x32x16_bf16 v[2:17], v[126:129], v[240:243], v[2:17]
	ds_read_b64_tr_b16 v[240:241], v181 offset:0x2200
	ds_read_b64_tr_b16 v[242:243], v181 offset:0x2a00
	v_mfma_f32_32x32x16_bf16 v[2:17], v[162:165], v[244:247], v[2:17]
	ds_read_b64_tr_b16 v[244:245], v181 offset:0x3200
	ds_read_b64_tr_b16 v[246:247], v181 offset:0x3a00
	s_waitcnt lgkmcnt(0)
	v_mfma_f32_32x32x16_bf16 v[50:65], v[118:121], v[172:175], v[50:65]
	v_max3_f32 v229, v229, v66, v67
	v_max3_f32 v229, v229, v68, v69
	v_max3_f32 v229, v229, v70, v71
	v_max3_f32 v229, v229, v72, v73
	v_max3_f32 v229, v229, v74, v75
	v_max3_f32 v172, v229, v76, v77
	v_max3_f32 v172, v172, v78, v79
	v_mfma_f32_32x32x16_bf16 v[50:65], v[122:125], v[236:239], v[50:65]
	v_max3_f32 v172, v172, v80, v81
	v_mov_b32_e32 v173, v172
	s_nop 1
	v_permlane32_swap_b32_e32 v172, v173
	v_max_f32_e32 v173, v173, v173
	v_max_f32_e32 v172, v172, v172
	v_max_f32_e32 v172, v172, v173
	v_mfma_f32_32x32x16_bf16 v[50:65], v[126:129], v[240:243], v[50:65]
	v_sub_f32_e32 v173, v172, v233
	ds_read_b64_tr_b16 v[236:237], v181 offset:0x400
	v_cmp_ge_f32_e32 vcc, s21, v173
	ds_read_b64_tr_b16 v[238:239], v181 offset:0xc00
	s_cmp_eq_u64 vcc, exec
	v_max_f32_e32 v173, v233, v233
	ds_read_b64_tr_b16 v[240:241], v181 offset:0x1400
	v_max_f32_e32 v172, v173, v172
	s_cselect_b64 vcc, -1, 0
	v_mfma_f32_32x32x16_bf16 v[50:65], v[162:165], v[244:247], v[50:65]
	ds_read_b64_tr_b16 v[242:243], v181 offset:0x1c00
	v_cndmask_b32_e32 v229, v172, v233, vcc
	ds_read_b64_tr_b16 v[244:245], v181 offset:0x2400
	v_sub_f32_e32 v172, v233, v229
	ds_read_b64_tr_b16 v[246:247], v181 offset:0x2c00
	v_mul_f32_e32 v172, 0x3dd53b94, v172
	ds_read_b64_tr_b16 v[248:249], v181 offset:0x3400
	v_exp_f32_e32 v172, v172
	ds_read_b64_tr_b16 v[250:251], v181 offset:0x3c00
	s_waitcnt lgkmcnt(0)
; #define SBAR() __builtin_amdgcn_sched_barrier(0)
; #define SWAIT() do { if constexpr (SD == 1) asm volatile("s_waitcnt vmcnt(0)" ::: "memory"); else asm volatile("s_waitcnt vmcnt(4)" ::: "memory"); } while (0)
; #define RESC(a) do { if (__any((a) < 1.f)) { if (hi == 0) al_l[r32] = (a); asm volatile("s_waitcnt lgkmcnt(0)" ::: "memory"); \
;     _Pragma("unroll") for (int d = 0; d < 4; ++d) _Pragma("unroll") for (int r = 0; r < 16; ++r) o[d][r] *= al_l[crow(r, hi)]; } } while (0)
; template <int DQK> __device__ __forceinline__ void pv_partialSM(f32x16* o, int vb, bf16x8 pa0, bf16x8 pa1, bf16x8 pa2, bf16x8 pa3,
;                                                                  f32x16& p0, f32x16& p1, float& m_reg, float& alpha) {
;     ...
;   const float mnC = -mn * C;
;   pv_one<2>(o[2], vb, pa0, pa1, pa2, pa3);
; #pragma unroll
;   for (int r = 0; r < 16; ++r) { p0[r] = fmaf(p0[r], C, mnC); p1[r] = fmaf(p1[r], C, mnC); }
;   pv_one<3>(o[3], vb, pa0, pa1, pa2, pa3);
; #pragma unroll
;   for (int r = 0; r < 16; ++r) p0[r] = __builtin_amdgcn_exp2f(p0[r]);
;   asm volatile("" : "+v"(p0), "+v"(p1));
;   SBAR();
; template <int DQK, int LDK> ...
;     ...
;     __syncthreads(); SWAIT(); SWRITE(1, SO);
;     RESC(alA); __syncthreads();
	v_mul_f32_e32 v174, 0xbdd53b94, v229
	v_mfma_f32_32x32x16_bf16 v[34:49], v[118:121], v[236:239], v[34:49]
	v_fmamk_f32 v175, v83, 0x3dd53b94, v174
	v_fmamk_f32 v173, v82, 0x3dd53b94, v174
	v_fma_f32 v82, v66, s36, v174
	v_fma_f32 v83, v67, s36, v174
	ds_read_b64_tr_b16 v[66:67], v181 offset:0x600
	v_fmamk_f32 v233, v84, 0x3dd53b94, v174
	v_fmamk_f32 v236, v85, 0x3dd53b94, v174
	v_fma_f32 v84, v68, s36, v174
	v_fma_f32 v85, v69, s36, v174
	v_mfma_f32_32x32x16_bf16 v[34:49], v[122:125], v[240:243], v[34:49]
	ds_read_b64_tr_b16 v[68:69], v181 offset:0xe00
	v_fmamk_f32 v237, v86, 0x3dd53b94, v174
	v_fmamk_f32 v238, v87, 0x3dd53b94, v174
	v_fma_f32 v86, v70, s36, v174
	v_fma_f32 v87, v71, s36, v174
	ds_read_b64_tr_b16 v[70:71], v181 offset:0x1600
	v_fmamk_f32 v239, v88, 0x3dd53b94, v174
	v_fmamk_f32 v240, v89, 0x3dd53b94, v174
	v_mfma_f32_32x32x16_bf16 v[34:49], v[126:129], v[244:247], v[34:49]
	v_fma_f32 v88, v72, s36, v174
	v_fma_f32 v89, v73, s36, v174
	ds_read_b64_tr_b16 v[72:73], v181 offset:0x1e00
	v_fmamk_f32 v241, v90, 0x3dd53b94, v174
	v_fmamk_f32 v242, v91, 0x3dd53b94, v174
	v_fma_f32 v90, v74, s36, v174
	v_fma_f32 v91, v75, s36, v174
	ds_read_b64_tr_b16 v[74:75], v181 offset:0x2600
	v_fmamk_f32 v243, v92, 0x3dd53b94, v174
	v_mfma_f32_32x32x16_bf16 v[34:49], v[162:165], v[248:251], v[34:49]
	v_fmamk_f32 v244, v93, 0x3dd53b94, v174
	v_fma_f32 v92, v76, s36, v174
	v_fma_f32 v93, v77, s36, v174
	ds_read_b64_tr_b16 v[76:77], v181 offset:0x2e00
	v_fmamk_f32 v245, v94, 0x3dd53b94, v174
	v_fmamk_f32 v246, v95, 0x3dd53b94, v174
	v_mov_b32_e32 v248, v174
	v_fma_f32 v94, v78, s36, v174
	v_fma_f32 v95, v79, s36, v174
	ds_read_b64_tr_b16 v[78:79], v181 offset:0x3600
	v_fmamk_f32 v247, v96, 0x3dd53b94, v174
	v_fmac_f32_e32 v248, 0x3dd53b94, v97
	v_fma_f32 v96, v80, s36, v174
	v_fma_f32 v97, v81, s36, v174
	ds_read_b64_tr_b16 v[80:81], v181 offset:0x3e00
	s_waitcnt lgkmcnt(0)
	v_mfma_f32_32x32x16_bf16 v[18:33], v[118:121], v[66:69], v[18:33]
	v_exp_f32_e32 v66, v173
	v_exp_f32_e32 v67, v175
	v_exp_f32_e32 v68, v233
	v_exp_f32_e32 v69, v236
	v_mfma_f32_32x32x16_bf16 v[18:33], v[122:125], v[70:73], v[18:33]
	v_exp_f32_e32 v70, v237
	v_exp_f32_e32 v71, v238
	v_exp_f32_e32 v72, v239
	v_exp_f32_e32 v73, v240
	v_mfma_f32_32x32x16_bf16 v[18:33], v[126:129], v[74:77], v[18:33]
	v_exp_f32_e32 v74, v241
	v_exp_f32_e32 v75, v242
	v_exp_f32_e32 v76, v243
	v_exp_f32_e32 v77, v244
	v_mfma_f32_32x32x16_bf16 v[18:33], v[162:165], v[78:81], v[18:33]
	v_exp_f32_e32 v78, v245
	v_exp_f32_e32 v79, v246
	v_exp_f32_e32 v80, v247
	v_exp_f32_e32 v81, v248
	s_barrier
	s_waitcnt vmcnt(0)
	v_cmp_gt_f32_e32 vcc, 1.0, v172
	s_waitcnt vmcnt(4)
	ds_write_b128 v185, v[98:101] offset:16384
	s_waitcnt vmcnt(2)
	ds_write_b128 v186, v[110:113] offset:16384
	ds_write_b128 v187, v[102:105] offset:50176
	s_waitcnt vmcnt(1)
	ds_write_b128 v187, v[106:109] offset:58880
	s_waitcnt vmcnt(0)
	ds_write_b128 v219, v[114:117]
	s_cbranch_vccz .LBB0_351
	s_and_saveexec_b64 s[2:3], s[40:41]
	ds_write_b32 v179, v172 offset:128
	s_or_b64 exec, exec, s[2:3]
	s_waitcnt lgkmcnt(0)
	v_add_u32_e32 v110, s14, v0
	ds_read_b128 v[98:101], v110 offset:224
	ds_read_b128 v[102:105], v110 offset:192
	ds_read_b128 v[106:109], v110 offset:160
	ds_read_b128 v[110:113], v110 offset:128
	s_waitcnt lgkmcnt(3)
	v_pk_mul_f32 v[14:15], v[14:15], v[98:99]
	s_waitcnt lgkmcnt(2)
	v_pk_mul_f32 v[10:11], v[10:11], v[102:103]
	s_waitcnt lgkmcnt(1)
	v_pk_mul_f32 v[6:7], v[6:7], v[106:107]
	v_pk_mul_f32 v[16:17], v[16:17], v[100:101]
	v_pk_mul_f32 v[12:13], v[12:13], v[104:105]
	v_pk_mul_f32 v[8:9], v[8:9], v[108:109]
	s_waitcnt lgkmcnt(0)
	v_pk_mul_f32 v[4:5], v[4:5], v[112:113]
	v_pk_mul_f32 v[2:3], v[2:3], v[110:111]
	v_pk_mul_f32 v[62:63], v[62:63], v[98:99]
	v_pk_mul_f32 v[58:59], v[58:59], v[102:103]
	v_pk_mul_f32 v[54:55], v[54:55], v[106:107]
	v_pk_mul_f32 v[64:65], v[64:65], v[100:101]
	v_pk_mul_f32 v[60:61], v[60:61], v[104:105]
	v_pk_mul_f32 v[56:57], v[56:57], v[108:109]
	v_pk_mul_f32 v[52:53], v[52:53], v[112:113]
	v_pk_mul_f32 v[50:51], v[50:51], v[110:111]
	v_pk_mul_f32 v[46:47], v[46:47], v[98:99]
	v_pk_mul_f32 v[42:43], v[42:43], v[102:103]
	v_pk_mul_f32 v[38:39], v[38:39], v[106:107]
	v_pk_mul_f32 v[48:49], v[48:49], v[100:101]
	v_pk_mul_f32 v[44:45], v[44:45], v[104:105]
	v_pk_mul_f32 v[40:41], v[40:41], v[108:109]
	v_pk_mul_f32 v[36:37], v[36:37], v[112:113]
	v_pk_mul_f32 v[34:35], v[34:35], v[110:111]
	v_pk_mul_f32 v[30:31], v[30:31], v[98:99]
	v_pk_mul_f32 v[26:27], v[26:27], v[102:103]
	v_pk_mul_f32 v[22:23], v[22:23], v[106:107]
	v_pk_mul_f32 v[32:33], v[32:33], v[100:101]
	v_pk_mul_f32 v[28:29], v[28:29], v[104:105]
	v_pk_mul_f32 v[24:25], v[24:25], v[108:109]
	v_pk_mul_f32 v[20:21], v[20:21], v[112:113]
	v_pk_mul_f32 v[18:19], v[18:19], v[110:111]

; __device__ __forceinline__ void finishSM(f32x16& p0, f32x16& p1, float alpha, float& l_reg, bf16x8& pa0, bf16x8& pa1, bf16x8& pa2, bf16x8& pa3) {
; #pragma unroll
;   for (int r = 0; r < 16; ++r) p1[r] = __builtin_amdgcn_exp2f(p1[r]);
;   float ps = 0;
; #pragma unroll
;   for (int r = 0; r < 16; ++r) ps += p0[r];
; #pragma unroll
;   for (int r = 0; r < 16; ++r) ps += p1[r];
;   { auto rr = __builtin_amdgcn_permlane32_swap(__float_as_uint(ps), __float_as_uint(ps), false, false);
;     ps = __uint_as_float(rr[0]) + __uint_as_float(rr[1]); }
;   l_reg = l_reg * alpha + ps;
;     ...
;   PK4(p0, 0, pa0); PK4(p0, 8, pa1); PK4(p1, 0, pa2); PK4(p1, 8, pa3);
;     ...
; }
; template <int DQK> __device__ __forceinline__ void qkt(f32x16& p0, f32x16& p1, const bf16_t* Ks, const char* KRs, const char* QRw, const bf16x8* qr, int r32, int hi) {
;   p0 = f32x16{}; p1 = f32x16{};
; #pragma unroll
;   for (int d0 = 0; d0 < 8; ++d0) { int cb = (d0 * 16 + hi * 8) * 2;
;     bf16x8 b0 = *reinterpret_cast<const bf16x8*>((const char*)Ks + KSWZ(r32, cb));
;     bf16x8 b1 = *reinterpret_cast<const bf16x8*>((const char*)Ks + KSWZ(32 + r32, cb));
;     p0 = __builtin_amdgcn_mfma_f32_32x32x16_bf16(b0, qr[d0], p0, 0, 0, 0);
;     p1 = __builtin_amdgcn_mfma_f32_32x32x16_bf16(b1, qr[d0], p1, 0, 0, 0); }
.LBB0_478:
	ds_read_b128 v[98:101], v218 offset:58880
	ds_read_b128 v[102:105], v218 offset:50176
	ds_read_b128 v[178:181], v218 offset:50208
	ds_read_b128 v[182:185], v218 offset:58912
	v_exp_f32_e32 v82, v82
	v_exp_f32_e32 v83, v83
	s_waitcnt lgkmcnt(2)
	v_mfma_f32_32x32x16_bf16 v[114:129], v[102:105], v[158:161], 0
	v_exp_f32_e32 v84, v84
	v_exp_f32_e32 v85, v85
	v_exp_f32_e32 v86, v86
	v_exp_f32_e32 v87, v87
	v_exp_f32_e32 v88, v88
	v_exp_f32_e32 v89, v89
	v_exp_f32_e32 v90, v90
	v_mfma_f32_32x32x16_bf16 v[98:113], v[98:101], v[158:161], 0
	v_exp_f32_e32 v91, v91
	v_exp_f32_e32 v92, v92
	v_exp_f32_e32 v93, v93
	v_exp_f32_e32 v94, v94
	v_exp_f32_e32 v95, v95
	v_exp_f32_e32 v96, v96
	v_exp_f32_e32 v97, v97
	s_waitcnt lgkmcnt(1)
	v_mfma_f32_32x32x16_bf16 v[114:129], v[178:181], v[154:157], v[114:129]
	s_waitcnt lgkmcnt(0)
	v_mfma_f32_32x32x16_bf16 v[98:113], v[182:185], v[154:157], v[98:113]
	ds_read_b128 v[178:181], v218 offset:50240
	ds_read_b128 v[182:185], v218 offset:58944
	s_waitcnt lgkmcnt(1)
	v_mfma_f32_32x32x16_bf16 v[114:129], v[178:181], v[150:153], v[114:129]
	s_waitcnt lgkmcnt(0)
	v_mfma_f32_32x32x16_bf16 v[98:113], v[182:185], v[150:153], v[98:113]
	ds_read_b128 v[178:181], v218 offset:50272
	ds_read_b128 v[182:185], v218 offset:58976
	s_waitcnt lgkmcnt(1)
	v_mfma_f32_32x32x16_bf16 v[114:129], v[178:181], v[146:149], v[114:129]
	s_waitcnt lgkmcnt(0)
	v_mfma_f32_32x32x16_bf16 v[98:113], v[182:185], v[146:149], v[98:113]
	ds_read_b128 v[178:181], v218 offset:50304
	ds_read_b128 v[182:185], v218 offset:59008
	s_waitcnt lgkmcnt(1)
	v_mfma_f32_32x32x16_bf16 v[114:129], v[178:181], v[142:145], v[114:129]
	s_waitcnt lgkmcnt(0)
	v_mfma_f32_32x32x16_bf16 v[98:113], v[182:185], v[142:145], v[98:113]
	ds_read_b128 v[178:181], v218 offset:50336
	ds_read_b128 v[182:185], v218 offset:59040
	s_waitcnt lgkmcnt(1)
	v_mfma_f32_32x32x16_bf16 v[114:129], v[178:181], v[138:141], v[114:129]
	s_waitcnt lgkmcnt(0)
	v_mfma_f32_32x32x16_bf16 v[98:113], v[182:185], v[138:141], v[98:113]
	ds_read_b128 v[178:181], v218 offset:50368
	ds_read_b128 v[182:185], v218 offset:59072
	s_waitcnt lgkmcnt(1)
	v_mfma_f32_32x32x16_bf16 v[114:129], v[178:181], v[134:137], v[114:129]
	s_waitcnt lgkmcnt(0)
	v_mfma_f32_32x32x16_bf16 v[98:113], v[182:185], v[134:137], v[98:113]
	ds_read_b128 v[178:181], v218 offset:50400
	ds_read_b128 v[182:185], v218 offset:59104
	s_waitcnt lgkmcnt(1)
	v_mfma_f32_32x32x16_bf16 v[114:129], v[178:181], v[130:133], v[114:129]
	v_add_f32_e32 v178, 0, v66
	v_add_f32_e32 v178, v67, v178
	v_add_f32_e32 v178, v68, v178
	v_add_f32_e32 v178, v69, v178
	v_add_f32_e32 v178, v70, v178
	v_add_f32_e32 v178, v71, v178
	v_add_f32_e32 v178, v72, v178
	v_add_f32_e32 v178, v73, v178
	v_add_f32_e32 v178, v74, v178
	v_add_f32_e32 v178, v75, v178
	v_add_f32_e32 v178, v76, v178
	v_add_f32_e32 v178, v77, v178
	v_add_f32_e32 v178, v78, v178
	v_add_f32_e32 v178, v79, v178
	v_add_f32_e32 v178, v80, v178
	v_add_f32_e32 v178, v81, v178
	v_add_f32_e32 v178, v82, v178
	v_add_f32_e32 v178, v83, v178
	v_add_f32_e32 v178, v84, v178
	v_add_f32_e32 v178, v85, v178
	v_add_f32_e32 v178, v86, v178
	v_add_f32_e32 v178, v87, v178
	v_add_f32_e32 v178, v88, v178
	v_add_f32_e32 v178, v89, v178
	v_add_f32_e32 v178, v90, v178
	v_add_f32_e32 v178, v91, v178
	s_waitcnt lgkmcnt(0)
	v_mfma_f32_32x32x16_bf16 v[98:113], v[182:185], v[130:133], v[98:113]
	v_add_f32_e32 v178, v92, v178
	v_add_f32_e32 v178, v93, v178
	v_add_f32_e32 v178, v94, v178
	v_add_f32_e32 v178, v95, v178
	v_add_f32_e32 v178, v96, v178
	v_add_f32_e32 v224, v97, v178
	v_mov_b32_e32 v225, v224
	s_nop 1
	v_permlane32_swap_b32_e32 v224, v225
	v_cvt_pk_bf16_f32 v66, v66, v67
	v_cvt_pk_bf16_f32 v67, v68, v69
	v_cvt_pk_bf16_f32 v68, v70, v71
	v_cvt_pk_bf16_f32 v69, v72, v73
	v_cvt_pk_bf16_f32 v70, v74, v75
	v_cvt_pk_bf16_f32 v71, v76, v77
	v_cvt_pk_bf16_f32 v72, v78, v79
	v_cvt_pk_bf16_f32 v73, v80, v81
	v_cvt_pk_bf16_f32 v74, v82, v83
	v_cvt_pk_bf16_f32 v75, v84, v85
	v_cvt_pk_bf16_f32 v76, v86, v87
	v_cvt_pk_bf16_f32 v77, v88, v89
	v_cvt_pk_bf16_f32 v78, v90, v91
	v_cvt_pk_bf16_f32 v79, v92, v93
	v_cvt_pk_bf16_f32 v80, v94, v95
	v_cvt_pk_bf16_f32 v81, v96, v97
	v_permlane32_swap_b32_e32 v66, v68
	v_permlane32_swap_b32_e32 v67, v69
	v_permlane32_swap_b32_e32 v70, v72
	v_permlane32_swap_b32_e32 v71, v73
	v_permlane32_swap_b32_e32 v74, v76
	v_permlane32_swap_b32_e32 v75, v77
	v_permlane32_swap_b32_e32 v78, v80
	v_permlane32_swap_b32_e32 v79, v81
	s_mov_b32 s2, 0xfffb8000
	v_add_co_u32_e32 v82, vcc, s2, v198
	s_mov_b32 s2, 0xfffd0000
	s_nop 0
	v_addc_co_u32_e32 v83, vcc, -1, v199, vcc
	v_add_co_u32_e32 v84, vcc, s2, v198
	s_nop 1
	v_addc_co_u32_e32 v85, vcc, -1, v199, vcc
	global_load_dwordx4 v[178:181], v[82:83], off
	global_load_dwordx4 v[182:185], v[82:83], off offset:-512
	global_load_dwordx4 v[190:193], v[84:85], off
	global_load_dwordx4 v[186:189], v[84:85], off offset:-512
	ds_read_b64_tr_b16 v[82:83], v217 offset:0
	ds_read_b64_tr_b16 v[84:85], v217 offset:0x800
	ds_read_b64_tr_b16 v[86:87], v217 offset:0x1000
	ds_read_b64_tr_b16 v[88:89], v217 offset:0x1800
	ds_read_b64_tr_b16 v[90:91], v217 offset:0x2000
	ds_read_b64_tr_b16 v[92:93], v217 offset:0x2800
	ds_read_b64_tr_b16 v[94:95], v217 offset:0x3000
	ds_read_b64_tr_b16 v[96:97], v217 offset:0x3800
	s_waitcnt lgkmcnt(0)
; #define SBAR() __builtin_amdgcn_sched_barrier(0)
; #define SWAIT() do { if constexpr (SD == 1) asm volatile("s_waitcnt vmcnt(0)" ::: "memory"); else asm volatile("s_waitcnt vmcnt(4)" ::: "memory"); } while (0)
; #define RESC(a) do { if (__any((a) < 1.f)) { if (hi == 0) al_l[r32] = (a); asm volatile("s_waitcnt lgkmcnt(0)" ::: "memory"); \
;     _Pragma("unroll") for (int d = 0; d < 4; ++d) _Pragma("unroll") for (int r = 0; r < 16; ++r) o[d][r] *= al_l[crow(r, hi)]; } } while (0)
; template <int DQK> __device__ __forceinline__ void pv_partialSM(f32x16* o, int vb, bf16x8 pa0, bf16x8 pa1, bf16x8 pa2, bf16x8 pa3,
;                                                                  f32x16& p0, f32x16& p1, float& m_reg, float& alpha) {
;     ...
;   pv_one<0>(o[0], vb, pa0, pa1, pa2, pa3);
;   float pmax = p0[0];
; #pragma unroll
;   for (int r = 1; r < 16; ++r) pmax = fmaxf(pmax, p0[r]);
;   pv_one<1>(o[1], vb, pa0, pa1, pa2, pa3);
; #pragma unroll
;   for (int r = 0; r < 16; ++r) pmax = fmaxf(pmax, p1[r]);
;   { auto rr = __builtin_amdgcn_permlane32_swap(__float_as_uint(pmax), __float_as_uint(pmax), false, false);
;     pmax = fmaxf(__uint_as_float(rr[0]), __uint_as_float(rr[1])); }
;   const bool keep = __all(pmax - m_reg <= THR / SCALE);
;   const float mn = keep ? m_reg : fmaxf(m_reg, pmax);
;   alpha = __builtin_amdgcn_exp2f((m_reg - mn) * C); m_reg = mn;
;   const float mnC = -mn * C;
;   pv_one<2>(o[2], vb, pa0, pa1, pa2, pa3);
; #pragma unroll
;   for (int r = 0; r < 16; ++r) { p0[r] = fmaf(p0[r], C, mnC); p1[r] = fmaf(p1[r], C, mnC); }
;   pv_one<3>(o[3], vb, pa0, pa1, pa2, pa3);
; #pragma unroll
;   for (int r = 0; r < 16; ++r) p0[r] = __builtin_amdgcn_exp2f(p0[r]);
;   asm volatile("" : "+v"(p0), "+v"(p1));
;   SBAR();
; template <int DQK, int LDK> ...
;     ...
;     __syncthreads(); SWAIT(); SWRITE(0, SE);
;     RESC(alB); __syncthreads();
	s_nop 0
	v_mfma_f32_32x32x16_bf16 v[2:17], v[66:69], v[82:85], v[2:17]
	v_max_f32_e32 v82, v115, v115
	v_max_f32_e32 v83, v114, v114
	v_max_f32_e32 v82, v83, v82
	v_max3_f32 v82, v82, v116, v117
	v_max3_f32 v82, v82, v118, v119
	v_max3_f32 v82, v82, v120, v121
	v_max3_f32 v82, v82, v122, v123
	v_mfma_f32_32x32x16_bf16 v[2:17], v[70:73], v[86:89], v[2:17]
	v_max3_f32 v82, v82, v124, v125
	v_max3_f32 v82, v82, v126, v127
	v_max3_f32 v223, v82, v128, v129
	ds_read_b64_tr_b16 v[82:83], v217 offset:0x200
	ds_read_b64_tr_b16 v[84:85], v217 offset:0xa00
	ds_read_b64_tr_b16 v[86:87], v217 offset:0x1200
	ds_read_b64_tr_b16 v[88:89], v217 offset:0x1a00
	v_mfma_f32_32x32x16_bf16 v[2:17], v[74:77], v[90:93], v[2:17]
	ds_read_b64_tr_b16 v[90:91], v217 offset:0x2200
	ds_read_b64_tr_b16 v[92:93], v217 offset:0x2a00
	v_mfma_f32_32x32x16_bf16 v[2:17], v[78:81], v[94:97], v[2:17]
	ds_read_b64_tr_b16 v[94:95], v217 offset:0x3200
	ds_read_b64_tr_b16 v[96:97], v217 offset:0x3a00
	s_waitcnt lgkmcnt(0)
	v_mfma_f32_32x32x16_bf16 v[50:65], v[66:69], v[82:85], v[50:65]
	v_max3_f32 v223, v223, v98, v99
	v_max3_f32 v223, v223, v100, v101
	v_max3_f32 v223, v223, v102, v103
	v_max3_f32 v223, v223, v104, v105
	v_max3_f32 v223, v223, v106, v107
	v_max3_f32 v82, v223, v108, v109
	v_max3_f32 v82, v82, v110, v111
	v_mfma_f32_32x32x16_bf16 v[50:65], v[70:73], v[86:89], v[50:65]
	v_max3_f32 v82, v82, v112, v113
	v_mov_b32_e32 v83, v82
	s_nop 1
	v_permlane32_swap_b32_e32 v82, v83
	v_max_f32_e32 v83, v83, v83
	v_max_f32_e32 v82, v82, v82
	v_max_f32_e32 v82, v82, v83
	v_sub_f32_e32 v83, v82, v226
	v_cmp_ge_f32_e32 vcc, s22, v83
	s_cmp_eq_u64 vcc, exec
	v_max_f32_e32 v83, v226, v226
	v_mfma_f32_32x32x16_bf16 v[50:65], v[74:77], v[90:93], v[50:65]
	v_max_f32_e32 v82, v83, v82
	s_cselect_b64 vcc, -1, 0
	v_cndmask_b32_e32 v223, v82, v226, vcc
	v_sub_f32_e32 v82, v226, v223
	v_mul_f32_e32 v82, 0x3e0293ee, v82
	v_exp_f32_e32 v227, v82
	ds_read_b64_tr_b16 v[82:83], v217 offset:0x400
	ds_read_b64_tr_b16 v[84:85], v217 offset:0xc00
	ds_read_b64_tr_b16 v[86:87], v217 offset:0x1400
	v_mfma_f32_32x32x16_bf16 v[50:65], v[78:81], v[94:97], v[50:65]
	ds_read_b64_tr_b16 v[88:89], v217 offset:0x1c00
	ds_read_b64_tr_b16 v[90:91], v217 offset:0x2400
	ds_read_b64_tr_b16 v[92:93], v217 offset:0x2c00
	ds_read_b64_tr_b16 v[94:95], v217 offset:0x3400
	ds_read_b64_tr_b16 v[96:97], v217 offset:0x3c00
	s_waitcnt lgkmcnt(0)
	v_mul_f32_e32 v226, 0xbe0293ee, v223
	v_mfma_f32_32x32x16_bf16 v[34:49], v[66:69], v[82:85], v[34:49]
	ds_read_b64_tr_b16 v[82:83], v217 offset:0x600
	ds_read_b64_tr_b16 v[84:85], v217 offset:0xe00
	v_mov_b32_e32 v243, v226
	v_fmamk_f32 v228, v114, 0x3e0293ee, v226
	v_fmamk_f32 v229, v115, 0x3e0293ee, v226
	v_fmamk_f32 v230, v116, 0x3e0293ee, v226
	v_fmamk_f32 v231, v117, 0x3e0293ee, v226
	v_mfma_f32_32x32x16_bf16 v[34:49], v[70:73], v[86:89], v[34:49]
	ds_read_b64_tr_b16 v[86:87], v217 offset:0x1600
	ds_read_b64_tr_b16 v[88:89], v217 offset:0x1e00
	v_fmamk_f32 v232, v118, 0x3e0293ee, v226
	v_fmamk_f32 v233, v119, 0x3e0293ee, v226
	v_fmamk_f32 v234, v120, 0x3e0293ee, v226
	v_fmamk_f32 v235, v121, 0x3e0293ee, v226
	v_fmamk_f32 v236, v122, 0x3e0293ee, v226
	v_mfma_f32_32x32x16_bf16 v[34:49], v[74:77], v[90:93], v[34:49]
	ds_read_b64_tr_b16 v[90:91], v217 offset:0x2600
	ds_read_b64_tr_b16 v[92:93], v217 offset:0x2e00
	v_fmamk_f32 v237, v123, 0x3e0293ee, v226
	v_fmamk_f32 v238, v124, 0x3e0293ee, v226
	v_fmamk_f32 v239, v125, 0x3e0293ee, v226
	v_fmamk_f32 v240, v126, 0x3e0293ee, v226
	v_fmamk_f32 v241, v127, 0x3e0293ee, v226
	v_mfma_f32_32x32x16_bf16 v[34:49], v[78:81], v[94:97], v[34:49]
	ds_read_b64_tr_b16 v[94:95], v217 offset:0x3600
	ds_read_b64_tr_b16 v[96:97], v217 offset:0x3e00
	s_waitcnt lgkmcnt(0)
	v_fmamk_f32 v242, v128, 0x3e0293ee, v226
	v_fmac_f32_e32 v243, 0x3e0293ee, v129
	v_fma_f32 v128, v112, s94, v226
	v_fma_f32 v129, v113, s94, v226
	v_fma_f32 v126, v110, s94, v226
	v_fma_f32 v127, v111, s94, v226
	v_fma_f32 v124, v108, s94, v226
	v_fma_f32 v125, v109, s94, v226
	v_fma_f32 v122, v106, s94, v226
	v_fma_f32 v123, v107, s94, v226
	v_fma_f32 v120, v104, s94, v226
	v_fma_f32 v121, v105, s94, v226
	v_fma_f32 v118, v102, s94, v226
	v_fma_f32 v119, v103, s94, v226
	v_fma_f32 v116, v100, s94, v226
	v_fma_f32 v117, v101, s94, v226
	v_fma_f32 v114, v98, s94, v226
	v_fma_f32 v115, v99, s94, v226
	v_mfma_f32_32x32x16_bf16 v[18:33], v[66:69], v[82:85], v[18:33]
	v_exp_f32_e32 v98, v228
	v_exp_f32_e32 v99, v229
	v_exp_f32_e32 v100, v230
	v_exp_f32_e32 v101, v231
	v_exp_f32_e32 v102, v232
	v_exp_f32_e32 v103, v233
	v_exp_f32_e32 v104, v234
	v_mfma_f32_32x32x16_bf16 v[18:33], v[70:73], v[86:89], v[18:33]
	v_exp_f32_e32 v105, v235
	v_exp_f32_e32 v106, v236
	v_exp_f32_e32 v107, v237
	v_exp_f32_e32 v108, v238
	v_exp_f32_e32 v109, v239
	v_exp_f32_e32 v110, v240
	v_exp_f32_e32 v111, v241
	v_mfma_f32_32x32x16_bf16 v[18:33], v[74:77], v[90:93], v[18:33]
	v_exp_f32_e32 v112, v242
	v_exp_f32_e32 v113, v243
	v_mfma_f32_32x32x16_bf16 v[18:33], v[78:81], v[94:97], v[18:33]
	s_barrier
	s_waitcnt vmcnt(4)
	v_cmp_gt_f32_e32 vcc, 1.0, v227
	s_waitcnt vmcnt(4)
	ds_write_b128 v219, v[162:165]
	ds_write_b128 v220, v[170:173]
	ds_write_b128 v221, v[174:177] offset:32768
	ds_write_b128 v221, v[166:169] offset:41472
	s_cbranch_vccz .LBB0_482
	s_and_saveexec_b64 s[2:3], s[40:41]
	ds_write_b32 v214, v227 offset:128
	s_or_b64 exec, exec, s[2:3]
	s_waitcnt lgkmcnt(0)
	v_add_u32_e32 v78, s14, v0
	ds_read_b128 v[66:69], v78 offset:224
	ds_read_b128 v[70:73], v78 offset:192
	ds_read_b128 v[74:77], v78 offset:160
	ds_read_b128 v[78:81], v78 offset:128
	s_waitcnt lgkmcnt(3)
	v_pk_mul_f32 v[14:15], v[14:15], v[66:67]
	s_waitcnt lgkmcnt(2)
	v_pk_mul_f32 v[10:11], v[10:11], v[70:71]
	s_waitcnt lgkmcnt(1)
	v_pk_mul_f32 v[6:7], v[6:7], v[74:75]
	v_pk_mul_f32 v[16:17], v[16:17], v[68:69]
	v_pk_mul_f32 v[12:13], v[12:13], v[72:73]
	v_pk_mul_f32 v[8:9], v[8:9], v[76:77]
	s_waitcnt lgkmcnt(0)
	v_pk_mul_f32 v[4:5], v[4:5], v[80:81]
	v_pk_mul_f32 v[2:3], v[2:3], v[78:79]
	v_pk_mul_f32 v[62:63], v[62:63], v[66:67]
	v_pk_mul_f32 v[58:59], v[58:59], v[70:71]
	v_pk_mul_f32 v[54:55], v[54:55], v[74:75]
	v_pk_mul_f32 v[64:65], v[64:65], v[68:69]
	v_pk_mul_f32 v[60:61], v[60:61], v[72:73]
	v_pk_mul_f32 v[56:57], v[56:57], v[76:77]
	v_pk_mul_f32 v[52:53], v[52:53], v[80:81]
	v_pk_mul_f32 v[50:51], v[50:51], v[78:79]
	v_pk_mul_f32 v[46:47], v[46:47], v[66:67]
	v_pk_mul_f32 v[42:43], v[42:43], v[70:71]
	v_pk_mul_f32 v[38:39], v[38:39], v[74:75]
	v_pk_mul_f32 v[48:49], v[48:49], v[68:69]
	v_pk_mul_f32 v[44:45], v[44:45], v[72:73]
	v_pk_mul_f32 v[40:41], v[40:41], v[76:77]
	v_pk_mul_f32 v[36:37], v[36:37], v[80:81]
	v_pk_mul_f32 v[34:35], v[34:35], v[78:79]
	v_pk_mul_f32 v[30:31], v[30:31], v[66:67]
	v_pk_mul_f32 v[26:27], v[26:27], v[70:71]
	v_pk_mul_f32 v[22:23], v[22:23], v[74:75]
	v_pk_mul_f32 v[32:33], v[32:33], v[68:69]
	v_pk_mul_f32 v[28:29], v[28:29], v[72:73]
	v_pk_mul_f32 v[24:25], v[24:25], v[76:77]
	v_pk_mul_f32 v[20:21], v[20:21], v[80:81]
	v_pk_mul_f32 v[18:19], v[18:19], v[78:79]

; #define SBAR() __builtin_amdgcn_sched_barrier(0)
; #define SWAIT() do { if constexpr (SD == 1) asm volatile("s_waitcnt vmcnt(0)" ::: "memory"); else asm volatile("s_waitcnt vmcnt(4)" ::: "memory"); } while (0)
; template <int DQK> __device__ __forceinline__ void pv_partialSM(f32x16* o, int vb, bf16x8 pa0, bf16x8 pa1, bf16x8 pa2, bf16x8 pa3,
;                                                                  f32x16& p0, f32x16& p1, float& m_reg, float& alpha) {
;     ...
;   pv_one<0>(o[0], vb, pa0, pa1, pa2, pa3);
;   float pmax = p0[0];
; #pragma unroll
;   for (int r = 1; r < 16; ++r) pmax = fmaxf(pmax, p0[r]);
;   pv_one<1>(o[1], vb, pa0, pa1, pa2, pa3);
; #pragma unroll
;   for (int r = 0; r < 16; ++r) pmax = fmaxf(pmax, p1[r]);
;   { auto rr = __builtin_amdgcn_permlane32_swap(__float_as_uint(pmax), __float_as_uint(pmax), false, false);
;     pmax = fmaxf(__uint_as_float(rr[0]), __uint_as_float(rr[1])); }
;   const bool keep = __all(pmax - m_reg <= THR / SCALE);
;   const float mn = keep ? m_reg : fmaxf(m_reg, pmax);
;   alpha = __builtin_amdgcn_exp2f((m_reg - mn) * C); m_reg = mn;
;   const float mnC = -mn * C;
;   pv_one<2>(o[2], vb, pa0, pa1, pa2, pa3);
; #pragma unroll
;   for (int r = 0; r < 16; ++r) { p0[r] = fmaf(p0[r], C, mnC); p1[r] = fmaf(p1[r], C, mnC); }
;   pv_one<3>(o[3], vb, pa0, pa1, pa2, pa3);
; #pragma unroll
;   for (int r = 0; r < 16; ++r) p0[r] = __builtin_amdgcn_exp2f(p0[r]);
;   asm volatile("" : "+v"(p0), "+v"(p1));
;   SBAR();
; template <int DQK, int LDK> ...
;     ...
;     if (SD == 1 || j + 3 < NT) SLOAD(SE, (j + 1 + SD) * KVBLK); SBAR();
;     pv_partialSM<DQK>(o, vb0 + (int)SHM_V, pa0, pa1, pa2, pa3, pA0, pA1, m_reg, alA);
;     __syncthreads(); SWAIT(); SWRITE(1, SO);
.LBB0_484:
	ds_read_b64_tr_b16 v[116:117], v216 offset:0
	ds_read_b64_tr_b16 v[118:119], v216 offset:0x800
	ds_read_b64_tr_b16 v[120:121], v216 offset:0x1000
	ds_read_b64_tr_b16 v[122:123], v216 offset:0x1800
	ds_read_b64_tr_b16 v[124:125], v216 offset:0x2000
	ds_read_b64_tr_b16 v[126:127], v216 offset:0x2800
	ds_read_b64_tr_b16 v[228:229], v216 offset:0x3000
	ds_read_b64_tr_b16 v[230:231], v216 offset:0x3800
	s_waitcnt lgkmcnt(0)
	s_nop 0
	v_mfma_f32_32x32x16_bf16 v[2:17], v[98:101], v[116:119], v[2:17]
	v_max_f32_e32 v116, v83, v83
	v_max_f32_e32 v117, v82, v82
	v_max_f32_e32 v116, v117, v116
	v_max3_f32 v116, v116, v84, v85
	v_max3_f32 v116, v116, v86, v87
	v_max3_f32 v116, v116, v88, v89
	v_max3_f32 v116, v116, v90, v91
	v_mfma_f32_32x32x16_bf16 v[2:17], v[102:105], v[120:123], v[2:17]
	v_max3_f32 v116, v116, v92, v93
	v_max3_f32 v116, v116, v94, v95
	v_max3_f32 v128, v116, v96, v97
	ds_read_b64_tr_b16 v[116:117], v216 offset:0x200
	ds_read_b64_tr_b16 v[118:119], v216 offset:0xa00
	ds_read_b64_tr_b16 v[120:121], v216 offset:0x1200
	ds_read_b64_tr_b16 v[122:123], v216 offset:0x1a00
	v_mfma_f32_32x32x16_bf16 v[2:17], v[106:109], v[124:127], v[2:17]
	ds_read_b64_tr_b16 v[124:125], v216 offset:0x2200
	ds_read_b64_tr_b16 v[126:127], v216 offset:0x2a00
	v_mfma_f32_32x32x16_bf16 v[2:17], v[110:113], v[228:231], v[2:17]
	ds_read_b64_tr_b16 v[228:229], v216 offset:0x3200
	ds_read_b64_tr_b16 v[230:231], v216 offset:0x3a00
	s_waitcnt lgkmcnt(0)
	v_mfma_f32_32x32x16_bf16 v[50:65], v[98:101], v[116:119], v[50:65]
	v_max3_f32 v128, v128, v66, v67
	v_max3_f32 v128, v128, v68, v69
	v_max3_f32 v128, v128, v70, v71
	v_max3_f32 v128, v128, v72, v73
	v_max3_f32 v128, v128, v74, v75
	v_max3_f32 v116, v128, v76, v77
	v_max3_f32 v116, v116, v78, v79
	v_mfma_f32_32x32x16_bf16 v[50:65], v[102:105], v[120:123], v[50:65]
	v_max3_f32 v116, v116, v80, v81
	v_mov_b32_e32 v117, v116
	s_nop 1
	v_permlane32_swap_b32_e32 v116, v117
	v_max_f32_e32 v117, v117, v117
	v_max_f32_e32 v116, v116, v116
	v_max_f32_e32 v116, v116, v117
	v_sub_f32_e32 v117, v116, v223
	v_cmp_ge_f32_e32 vcc, s22, v117
	s_cmp_eq_u64 vcc, exec
	v_max_f32_e32 v117, v223, v223
	v_mfma_f32_32x32x16_bf16 v[50:65], v[106:109], v[124:127], v[50:65]
	v_max_f32_e32 v116, v117, v116
	s_cselect_b64 vcc, -1, 0
	v_cndmask_b32_e32 v226, v116, v223, vcc
	v_sub_f32_e32 v116, v223, v226
	v_mul_f32_e32 v116, 0x3e0293ee, v116
	v_exp_f32_e32 v223, v116
	ds_read_b64_tr_b16 v[116:117], v216 offset:0x400
	ds_read_b64_tr_b16 v[118:119], v216 offset:0xc00
	ds_read_b64_tr_b16 v[120:121], v216 offset:0x1400
	v_mfma_f32_32x32x16_bf16 v[50:65], v[110:113], v[228:231], v[50:65]
	ds_read_b64_tr_b16 v[122:123], v216 offset:0x1c00
	ds_read_b64_tr_b16 v[124:125], v216 offset:0x2400
	ds_read_b64_tr_b16 v[126:127], v216 offset:0x2c00
	ds_read_b64_tr_b16 v[228:229], v216 offset:0x3400
	ds_read_b64_tr_b16 v[230:231], v216 offset:0x3c00
	s_waitcnt lgkmcnt(0)
	v_mul_f32_e32 v128, 0xbe0293ee, v226
	v_mfma_f32_32x32x16_bf16 v[34:49], v[98:101], v[116:119], v[34:49]
	v_fmamk_f32 v129, v94, 0x3e0293ee, v128
	v_fmamk_f32 v116, v82, 0x3e0293ee, v128
	v_fmamk_f32 v117, v83, 0x3e0293ee, v128
	v_fma_f32 v82, v66, s94, v128
	v_fma_f32 v83, v67, s94, v128
	ds_read_b64_tr_b16 v[66:67], v216 offset:0x600
	v_fmamk_f32 v118, v84, 0x3e0293ee, v128
	v_fmamk_f32 v119, v85, 0x3e0293ee, v128
	v_mfma_f32_32x32x16_bf16 v[34:49], v[102:105], v[120:123], v[34:49]
	v_fma_f32 v84, v68, s94, v128
	v_fma_f32 v85, v69, s94, v128
	ds_read_b64_tr_b16 v[68:69], v216 offset:0xe00
	v_fmamk_f32 v120, v86, 0x3e0293ee, v128
	v_fmamk_f32 v121, v87, 0x3e0293ee, v128
	v_fma_f32 v86, v70, s94, v128
	v_fma_f32 v87, v71, s94, v128
	ds_read_b64_tr_b16 v[70:71], v216 offset:0x1600
	v_fmamk_f32 v122, v88, 0x3e0293ee, v128
	v_mfma_f32_32x32x16_bf16 v[34:49], v[106:109], v[124:127], v[34:49]
	v_fmamk_f32 v123, v89, 0x3e0293ee, v128
	v_fma_f32 v88, v72, s94, v128
	v_fma_f32 v89, v73, s94, v128
	ds_read_b64_tr_b16 v[72:73], v216 offset:0x1e00
	v_fmamk_f32 v124, v90, 0x3e0293ee, v128
	v_fmamk_f32 v125, v91, 0x3e0293ee, v128
	v_fma_f32 v90, v74, s94, v128
	v_fma_f32 v91, v75, s94, v128
	ds_read_b64_tr_b16 v[74:75], v216 offset:0x2600
	v_mfma_f32_32x32x16_bf16 v[34:49], v[110:113], v[228:231], v[34:49]
	v_fmamk_f32 v126, v92, 0x3e0293ee, v128
	v_fmamk_f32 v127, v93, 0x3e0293ee, v128
	v_fma_f32 v92, v76, s94, v128
	v_fma_f32 v93, v77, s94, v128
	ds_read_b64_tr_b16 v[76:77], v216 offset:0x2e00
	v_fmamk_f32 v228, v95, 0x3e0293ee, v128
	v_mov_b32_e32 v230, v128
	v_fma_f32 v94, v78, s94, v128
	v_fma_f32 v95, v79, s94, v128
	ds_read_b64_tr_b16 v[78:79], v216 offset:0x3600
	v_fmamk_f32 v229, v96, 0x3e0293ee, v128
	v_fmac_f32_e32 v230, 0x3e0293ee, v97
	v_fma_f32 v96, v80, s94, v128
	v_fma_f32 v97, v81, s94, v128
	ds_read_b64_tr_b16 v[80:81], v216 offset:0x3e00
	s_waitcnt lgkmcnt(0)
	v_mfma_f32_32x32x16_bf16 v[18:33], v[98:101], v[66:69], v[18:33]
	v_exp_f32_e32 v66, v116
	v_exp_f32_e32 v67, v117
	v_exp_f32_e32 v68, v118
	v_exp_f32_e32 v69, v119
	v_mfma_f32_32x32x16_bf16 v[18:33], v[102:105], v[70:73], v[18:33]
	v_exp_f32_e32 v70, v120
	v_exp_f32_e32 v71, v121
	v_exp_f32_e32 v72, v122
	v_exp_f32_e32 v73, v123
	v_mfma_f32_32x32x16_bf16 v[18:33], v[106:109], v[74:77], v[18:33]
	v_exp_f32_e32 v74, v124
	v_exp_f32_e32 v75, v125
	v_exp_f32_e32 v76, v126
	v_exp_f32_e32 v77, v127
	v_mfma_f32_32x32x16_bf16 v[18:33], v[110:113], v[78:81], v[18:33]
	v_exp_f32_e32 v78, v129
	v_exp_f32_e32 v79, v228
	v_exp_f32_e32 v80, v229
	v_exp_f32_e32 v81, v230
	s_barrier
	s_waitcnt vmcnt(4)
	v_cmp_gt_f32_e32 vcc, 1.0, v223
	s_cmp_ge_u32 s16, s15
	s_cbranch_scc0 .Lgqa_w1
	s_waitcnt vmcnt(0)
